# P5: the wave's S-state fragments (same for the workgroup's four slices) loaded once into v[192:251] and kept across items: 15 of 16 fragment re-reads per item dropped
# speedup vs baseline: 1.0097x; 1.0097x over previous
.LBB0_426:
	s_add_u32 s22, s16, 0x2000000
	s_addc_u32 s23, s17, 0
	s_add_u32 s44, s16, 0xb000000
	s_addc_u32 s45, s17, 0
	s_cmpk_lg_i32 s52, 0x100
	s_cselect_b64 s[24:25], -1, 0
	s_lshl_b32 s4, s54, 5
	s_and_b32 s47, s4, 32
	s_lshl_b32 s4, s31, 2
	s_add_i32 s48, s4, 0
	s_lshl_b32 s4, s54, 4
	s_add_i32 s51, s54, 8
	s_load_dwordx2 s[14:15], s[18:19], 0x28
	s_load_dwordx2 s[20:21], s[18:19], 0x68
	s_and_b32 s49, s4, 0x3fffffe0
	s_lshl_b32 s4, s51, 4
	s_and_b32 s57, s4, 0x7fffffe0
	s_lshl_b32 s4, s33, 4
	s_add_i32 s60, s4, 16
	s_lshl_b32 s4, s33, 6
	s_add_i32 s61, s4, 64
	s_lshl_b32 s4, s33, 5
	v_cndmask_b32_e64 v2, 0, 1, s[24:25]
	s_ashr_i32 s46, s31, 31
	s_mov_b32 s27, 0
	s_add_i32 s48, s48, 0x20800
	s_lshl_b32 s50, s49, 1
	s_lshl_b32 s59, s57, 1
	s_add_i32 s62, s4, 32
	v_mov_b32_e32 v163, 0
	s_movk_i32 s63, 0x1000
	s_movk_i32 s64, 0x2000
	s_movk_i32 s65, 0x3000
	s_movk_i32 s66, 0x1800
	v_mov_b64_e32 v[164:165], s[12:13]
	s_movk_i32 s67, 0xf0
	s_mov_b64 s[28:29], 0x400
	v_cmp_ne_u32_e64 s[4:5], 1, v2
	s_movk_i32 s68, 0x110
	s_mov_b32 s69, 0x20000
	s_movk_i32 s70, 0x210
	s_mov_b32 s30, 0x3b000000
	s_mov_b32 s34, 0x358637bd
	s_mov_b32 s71, 0x800000
	s_mov_b32 s98, 1
	s_branch .LBB0_428

.LBB0_428:
	s_ashr_i32 s74, s33, 4
	s_bfe_u32 s73, s33, 0x20002
	s_lshl_b32 s6, s74, 2
	s_or_b32 s6, s6, s73
	s_ashr_i32 s7, s6, 31
	s_lshl_b64 s[6:7], s[6:7], 9
	v_mov_b32_e32 v170, v168
	s_add_u32 s6, s6, s31
	s_addc_u32 s7, s7, s46
	v_and_b32_e32 v169, 15, v170
	v_or_b32_e32 v2, s6, v169
	v_mov_b32_e32 v3, s7
	v_lshlrev_b64 v[2:3], 8, v[2:3]
	v_lshl_add_u64 v[2:3], s[22:23], 0, v[2:3]
	v_and_b32_e32 v162, 48, v170
	v_lshl_add_u64 v[2:3], v[2:3], 0, v[162:163]
	v_add_co_u32_e32 v4, vcc, s63, v2
	v_ashrrev_i32_e32 v108, 4, v170
	s_nop 0
	v_addc_co_u32_e32 v5, vcc, 0, v3, vcc
	v_add_co_u32_e32 v6, vcc, s64, v2
	s_lshl_b32 s72, s74, 8
	s_nop 0
	v_addc_co_u32_e32 v7, vcc, 0, v3, vcc
	v_add_co_u32_e32 v8, vcc, s65, v2
	s_nop 1
	v_addc_co_u32_e32 v9, vcc, 0, v3, vcc
	s_cmp_eq_u32 s98, 0
	s_cbranch_scc1 .Lp5c_skip
	global_load_dwordx4 v[192:195], v[2:3], off
	global_load_dwordx4 v[196:199], v[2:3], off offset:64
	global_load_dwordx4 v[200:203], v[6:7], off
	global_load_dwordx4 v[204:207], v[6:7], off offset:64
	global_load_dwordx4 v[208:211], v[4:5], off offset:64
	global_load_dwordx4 v[212:215], v[4:5], off offset:128
	global_load_dwordx4 v[216:219], v[8:9], off offset:64
	global_load_dwordx4 v[220:223], v[8:9], off offset:128
	global_load_dwordx4 v[224:227], v[2:3], off offset:128
	global_load_dwordx4 v[228:231], v[2:3], off offset:192
	global_load_dwordx4 v[232:235], v[8:9], off
	global_load_dwordx4 v[236:239], v[4:5], off offset:192
	global_load_dwordx4 v[240:243], v[6:7], off offset:128
	global_load_dwordx4 v[244:247], v[6:7], off offset:192
	global_load_dwordx4 v[248:251], v[6:7], off offset:-4096
.Lp5c_skip:
	global_load_dwordx4 v[50:53], v[8:9], off offset:192
	v_add_u32_e32 v2, s72, v108
	v_mad_i64_i32 v[2:3], s[6:7], v2, s66, v[164:165]
	s_lshl_b32 s26, s73, 8
	v_lshlrev_b32_e32 v4, 4, v170
	v_lshl_add_u64 v[2:3], v[2:3], 0, s[26:27]
	v_and_b32_e32 v4, 0xf0, v4
	v_mov_b32_e32 v5, v163
	v_lshl_add_u64 v[2:3], v[2:3], 0, v[4:5]
	v_lshl_add_u64 v[106:107], v[2:3], 0, s[28:29]
	s_and_b64 vcc, exec, s[4:5]
	v_mov_b32_e32 v2, 0
	v_mov_b32_e32 v3, 0
	v_mov_b32_e32 v4, 0
	v_mov_b32_e32 v5, 0
	s_cbranch_vccnz .LBB0_430
	global_load_dwordx4 v[2:5], v[106:107], off

.LBB0_444:
	v_xor_b32_e32 v106, v108, v170
	v_lshlrev_b32_e32 v106, 4, v106
	v_lshlrev_b32_e32 v107, 8, v108
	v_and_or_b32 v106, v106, s67, v107
	v_add_u32_e32 v107, 0, v106
	s_and_b64 vcc, exec, s[4:5]
	s_cmp_eq_u32 s98, 0
	s_cbranch_scc1 .Lp5c_w2
	s_waitcnt vmcnt(17)
	ds_write_b128 v107, v[22:25]
	s_waitcnt vmcnt(16)
	ds_write_b128 v107, v[18:21] offset:8192
	s_branch .Lp5c_wj
.Lp5c_w2:
	s_waitcnt vmcnt(2)
	ds_write_b128 v107, v[22:25]
	s_waitcnt vmcnt(1)
	ds_write_b128 v107, v[18:21] offset:8192
.Lp5c_wj:
	s_mov_b32 s98, 0
	s_cbranch_vccnz .Lp5_kpersist
	v_add_u32_e32 v107, 0x10800, v107
	s_waitcnt vmcnt(0)
	ds_write_b128 v107, v[2:5]
	ds_write_b128 v107, v[10:13] offset:8192
	s_and_b64 vcc, exec, s[6:7]
	s_cbranch_vccz .LBB0_477

.LBB0_456:
	v_bfe_u32 v138, v170, 4, 2
	v_lshl_add_u32 v139, v169, 8, 0
	v_xor_b32_e32 v2, v138, v169
	s_lshl_b32 s6, s74, 3
	v_lshl_add_u32 v98, v2, 4, v139
	s_ashr_i32 s7, s6, 31
	s_waitcnt lgkmcnt(0)
	s_barrier
	ds_read_b128 v[2:5], v98
	ds_read_b128 v[10:13], v98 offset:4096
	ds_read_b128 v[90:93], v98 offset:8192
	ds_read_b128 v[98:101], v98 offset:12288
	s_lshl_b64 s[6:7], s[6:7], 11
	s_lshl_b32 s73, s73, 9
	s_add_u32 s8, s73, s31
	s_addc_u32 s9, 0, s46
	s_add_u32 s6, s8, s6
	s_addc_u32 s7, s9, s7
	s_waitcnt lgkmcnt(3)
	s_waitcnt vmcnt(0)
	v_mfma_f32_16x16x32_bf16 v[6:9], v[192:195], v[2:5], 0
	v_mov_b32_e32 v123, s7
	v_or_b32_e32 v122, s6, v169
	v_lshlrev_b32_e32 v124, 3, v138
	s_waitcnt lgkmcnt(2)
	v_mfma_f32_16x16x32_bf16 v[14:17], v[192:195], v[10:13], 0
	v_lshlrev_b64 v[122:123], 6, v[122:123]
	v_lshl_add_u64 v[122:123], s[20:21], 0, v[122:123]
	v_lshlrev_b32_e32 v124, 1, v124
	s_waitcnt lgkmcnt(1)
	v_mfma_f32_16x16x32_bf16 v[94:97], v[192:195], v[90:93], 0
	v_mov_b32_e32 v125, v163
	v_lshl_add_u64 v[166:167], v[122:123], 0, v[124:125]
	s_waitcnt lgkmcnt(0)
	v_mfma_f32_16x16x32_bf16 v[66:69], v[192:195], v[98:101], 0
	v_mfma_f32_16x16x32_bf16 v[102:105], v[248:251], v[2:5], 0
	v_mfma_f32_16x16x32_bf16 v[106:109], v[248:251], v[10:13], 0
	v_mfma_f32_16x16x32_bf16 v[110:113], v[248:251], v[90:93], 0
	v_mfma_f32_16x16x32_bf16 v[86:89], v[248:251], v[98:101], 0
	v_mfma_f32_16x16x32_bf16 v[114:117], v[200:203], v[2:5], 0
	v_mfma_f32_16x16x32_bf16 v[118:121], v[200:203], v[10:13], 0
	v_mfma_f32_16x16x32_bf16 v[140:143], v[200:203], v[90:93], 0
	v_mfma_f32_16x16x32_bf16 v[46:49], v[200:203], v[98:101], 0
	v_mfma_f32_16x16x32_bf16 v[2:5], v[232:235], v[2:5], 0
	v_mfma_f32_16x16x32_bf16 v[10:13], v[232:235], v[10:13], 0
	v_mfma_f32_16x16x32_bf16 v[90:93], v[232:235], v[90:93], 0
	v_mfma_f32_16x16x32_bf16 v[42:45], v[232:235], v[98:101], 0
	global_load_dwordx4 v[134:137], v[166:167], off
	global_load_dwordx4 v[130:133], v[166:167], off offset:1024
	global_load_dwordx4 v[126:129], v[166:167], off offset:2048
	global_load_dwordx4 v[122:125], v[166:167], off offset:3072
	v_bitop3_b32 v98, v138, v169, 4 bitop3:0x36
	v_lshl_add_u32 v152, v98, 4, v139
	ds_read_b128 v[98:101], v152
	ds_read_b128 v[144:147], v152 offset:4096
	ds_read_b128 v[148:151], v152 offset:8192
	ds_read_b128 v[152:155], v152 offset:12288
	s_waitcnt lgkmcnt(3)
	v_mfma_f32_16x16x32_bf16 v[6:9], v[196:199], v[98:101], v[6:9]
	s_waitcnt lgkmcnt(2)
	v_mfma_f32_16x16x32_bf16 v[14:17], v[196:199], v[144:147], v[14:17]
	s_waitcnt lgkmcnt(1)
	v_mfma_f32_16x16x32_bf16 v[94:97], v[196:199], v[148:151], v[94:97]
	s_waitcnt lgkmcnt(0)
	v_mfma_f32_16x16x32_bf16 v[34:37], v[196:199], v[152:155], v[66:69]
	v_mfma_f32_16x16x32_bf16 v[66:69], v[208:211], v[98:101], v[102:105]
	v_mfma_f32_16x16x32_bf16 v[102:105], v[208:211], v[144:147], v[106:109]
	v_mfma_f32_16x16x32_bf16 v[156:159], v[208:211], v[148:151], v[110:113]
	v_mfma_f32_16x16x32_bf16 v[38:41], v[208:211], v[152:155], v[86:89]
	v_mfma_f32_16x16x32_bf16 v[86:89], v[204:207], v[98:101], v[114:117]
	v_mfma_f32_16x16x32_bf16 v[98:101], v[216:219], v[98:101], v[2:5]
	v_mfma_f32_16x16x32_bf16 v[172:175], v[204:207], v[144:147], v[118:121]
	v_mfma_f32_16x16x32_bf16 v[140:143], v[204:207], v[148:151], v[140:143]
	v_mfma_f32_16x16x32_bf16 v[176:179], v[204:207], v[152:155], v[46:49]
	v_mfma_f32_16x16x32_bf16 v[144:147], v[216:219], v[144:147], v[10:13]
	v_mfma_f32_16x16x32_bf16 v[148:151], v[216:219], v[148:151], v[90:93]
	v_mfma_f32_16x16x32_bf16 v[152:155], v[216:219], v[152:155], v[42:45]
	v_add_co_u32_e32 v2, vcc, s69, v166
	s_nop 1
	v_addc_co_u32_e32 v3, vcc, 0, v167, vcc
	global_load_dwordx4 v[118:121], v[2:3], off
	global_load_dwordx4 v[114:117], v[2:3], off offset:1024
	global_load_dwordx4 v[110:113], v[2:3], off offset:2048
	global_load_dwordx4 v[106:109], v[2:3], off offset:3072
	v_bitop3_b32 v2, v138, v169, 8 bitop3:0x36
	v_lshl_add_u32 v26, v2, 4, v139
	ds_read_b128 v[90:93], v26
	ds_read_b128 v[180:183], v26 offset:4096
	ds_read_b128 v[184:187], v26 offset:8192
	ds_read_b128 v[188:191], v26 offset:12288
	s_waitcnt lgkmcnt(3)
	v_mfma_f32_16x16x32_bf16 v[2:5], v[224:227], v[90:93], v[6:9]
	s_waitcnt lgkmcnt(2)
	v_mfma_f32_16x16x32_bf16 v[6:9], v[224:227], v[180:183], v[14:17]
	s_waitcnt lgkmcnt(1)
	v_mfma_f32_16x16x32_bf16 v[10:13], v[224:227], v[184:187], v[94:97]
	s_waitcnt lgkmcnt(0)
	v_mfma_f32_16x16x32_bf16 v[14:17], v[224:227], v[188:191], v[34:37]
	v_mfma_f32_16x16x32_bf16 v[26:29], v[212:215], v[90:93], v[66:69]
	v_mfma_f32_16x16x32_bf16 v[30:33], v[212:215], v[180:183], v[102:105]
	v_mfma_f32_16x16x32_bf16 v[34:37], v[212:215], v[184:187], v[156:159]
	v_mfma_f32_16x16x32_bf16 v[38:41], v[212:215], v[188:191], v[38:41]
	v_mfma_f32_16x16x32_bf16 v[42:45], v[240:243], v[90:93], v[86:89]
	v_mfma_f32_16x16x32_bf16 v[46:49], v[240:243], v[180:183], v[172:175]
	v_mfma_f32_16x16x32_bf16 v[66:69], v[240:243], v[184:187], v[140:143]
	v_mfma_f32_16x16x32_bf16 v[86:89], v[240:243], v[188:191], v[176:179]
	v_mfma_f32_16x16x32_bf16 v[90:93], v[220:223], v[90:93], v[98:101]
	v_mfma_f32_16x16x32_bf16 v[94:97], v[220:223], v[180:183], v[144:147]
	v_mfma_f32_16x16x32_bf16 v[98:101], v[220:223], v[184:187], v[148:151]
	v_mfma_f32_16x16x32_bf16 v[102:105], v[220:223], v[188:191], v[152:155]
	s_cmp_lg_u32 s75, 0
	s_cselect_b64 s[6:7], -1, 0
	s_cmp_eq_u32 s75, 0
	s_cbranch_scc1 .LBB0_458
	v_add_co_u32_e32 v70, vcc, 0x40000, v166
	s_nop 1
	v_addc_co_u32_e32 v71, vcc, 0, v167, vcc
	global_load_dwordx4 v[82:85], v[70:71], off
	global_load_dwordx4 v[74:77], v[70:71], off offset:1024
	global_load_dwordx4 v[78:81], v[70:71], off offset:2048
	s_nop 0
	global_load_dwordx4 v[70:73], v[70:71], off offset:3072
.LBB0_458:
	v_bitop3_b32 v138, v138, v169, 12 bitop3:0x36
	v_lshl_add_u32 v150, v138, 4, v139
	ds_read_b128 v[138:141], v150
	ds_read_b128 v[142:145], v150 offset:4096
	ds_read_b128 v[146:149], v150 offset:8192
	ds_read_b128 v[150:153], v150 offset:12288
	s_waitcnt lgkmcnt(3)
	v_mfma_f32_16x16x32_bf16 v[2:5], v[228:231], v[138:141], v[2:5]
	s_waitcnt lgkmcnt(2)
	v_mfma_f32_16x16x32_bf16 v[6:9], v[228:231], v[142:145], v[6:9]
	s_waitcnt lgkmcnt(1)
	v_mfma_f32_16x16x32_bf16 v[10:13], v[228:231], v[146:149], v[10:13]
	s_waitcnt lgkmcnt(0)
	v_mfma_f32_16x16x32_bf16 v[14:17], v[228:231], v[150:153], v[14:17]
	v_mfma_f32_16x16x32_bf16 v[26:29], v[236:239], v[138:141], v[26:29]
	v_mfma_f32_16x16x32_bf16 v[30:33], v[236:239], v[142:145], v[30:33]
	v_mfma_f32_16x16x32_bf16 v[34:37], v[236:239], v[146:149], v[34:37]
	v_mfma_f32_16x16x32_bf16 v[38:41], v[236:239], v[150:153], v[38:41]
	v_mfma_f32_16x16x32_bf16 v[42:45], v[244:247], v[138:141], v[42:45]
	v_mfma_f32_16x16x32_bf16 v[46:49], v[244:247], v[142:145], v[46:49]
	v_mfma_f32_16x16x32_bf16 v[66:69], v[244:247], v[146:149], v[66:69]
	v_mfma_f32_16x16x32_bf16 v[86:89], v[244:247], v[150:153], v[86:89]
	v_mfma_f32_16x16x32_bf16 v[90:93], v[50:53], v[138:141], v[90:93]
	v_mfma_f32_16x16x32_bf16 v[94:97], v[50:53], v[142:145], v[94:97]
	v_mfma_f32_16x16x32_bf16 v[98:101], v[50:53], v[146:149], v[98:101]
	v_mfma_f32_16x16x32_bf16 v[102:105], v[50:53], v[150:153], v[102:105]
	v_cndmask_b32_e64 v138, 0, 1, s[6:7]
	v_cmp_ne_u32_e64 s[10:11], 1, v138
	s_andn2_b64 vcc, exec, s[6:7]
	s_cbranch_vccnz .LBB0_460
	v_add_co_u32_e32 v50, vcc, 0x60000, v166
	s_nop 1
	v_addc_co_u32_e32 v51, vcc, 0, v167, vcc
	global_load_dwordx4 v[62:65], v[50:51], off
	global_load_dwordx4 v[58:61], v[50:51], off offset:1024
	global_load_dwordx4 v[54:57], v[50:51], off offset:2048
	s_nop 0
	global_load_dwordx4 v[50:53], v[50:51], off offset:3072
